# in-proj V^T tiles: permlane32_swap pairs the two 8-byte pieces so each lane stores one dwordx4
# speedup vs baseline: 1.0326x; 1.0012x over previous
; #define G8_STAGE(bufoff, gbase, voff) do { _Pragma("unroll") for (int _i = 0; _i < 2; ++_i) \
;     __builtin_amdgcn_global_load_lds((const unsigned*)((const char*)(gbase) + (voff)[_i]), (G8_LAS unsigned*)(lds + (bufoff) + ldsw + _i * 8192), 16, 0, 0); } while (0)
; #define G8_LDA(dst, b, h) do { _Pragma("unroll") for (int m = 0; m < 4; ++m) _Pragma("unroll") for (int k = 0; k < 2; ++k) dst[m][k] = *(const G8_LAS bf16x8*)(lds + G8_SA(b, h) + aoff + m * 2048 + k * 1024); } while (0)
; #define G8_LDB(dst, b, h) do { _Pragma("unroll") for (int n = 0; n < 2; ++n) _Pragma("unroll") for (int k = 0; k < 2; ++k) dst[n][k] = *(const G8_LAS bf16x8*)(lds + G8_SB(b, h) + boff + n * 2048 + k * 1024); } while (0)
; #define G8_MMA(ai, bj, At, Bt) do { __builtin_amdgcn_s_setprio(1); _Pragma("unroll") for (int m = 0; m < 4; ++m) _Pragma("unroll") for (int n = 0; n < 2; ++n) _Pragma("unroll") for (int k = 0; k < 2; ++k) \
;     acc[ai][bj][m][n] = __builtin_amdgcn_mfma_f32_16x16x32_bf16(Bt[n][k], At[m][k], acc[ai][bj][m][n], 0, 0, 0); __builtin_amdgcn_s_setprio(0); } while (0)
; #define G8_WAIT_V(n) asm volatile("s_waitcnt vmcnt(" #n ")" ::: "memory")
; #define G8_WAIT_L(n) asm volatile("s_waitcnt lgkmcnt(" #n ")" ::: "memory")
; #define G8_BAR __builtin_amdgcn_s_barrier()
; #define G8_SCHED __builtin_amdgcn_sched_barrier(0)
; template <int LD, class Sched, class Epi>
; DI void gemm_phase(G8_LAS unsigned char* lds, const int K, const Sched& S, const Epi& E) {
;     ...
;       G8_LDB(B0, 0, 0); G8_SCHED; G8_LDA(At, 0, 0); G8_STAGE(G8_SA(1, 1), a1 + hstep, voffA);
;       G8_WAIT_L(8); G8_BAR; G8_WAIT_L(0); G8_MMA(0, 0, At, B0); G8_BAR; G8_SCHED;
;       G8_LDB(B1, 0, 1); G8_STAGE(G8_SB(0, 0), b2, voffB);
;       G8_BAR; G8_WAIT_L(0); G8_MMA(0, 1, At, B1); G8_BAR;
;       G8_LDA(At, 0, 1); G8_STAGE(G8_SA(0, 0), a2, voffA);
;       G8_BAR; G8_WAIT_L(0); G8_MMA(1, 0, At, B0); G8_BAR; G8_SCHED;
;       G8_STAGE(G8_SB(0, 1), b2 + hstep, voffB);
;       G8_WAIT_V(6); G8_BAR; G8_MMA(1, 1, At, B1); G8_BAR;
.LBB0_92:
	ds_read_b128 v[130:133], v157
	ds_read_b128 v[162:165], v157 offset:1024
	ds_read_b128 v[166:169], v157 offset:2048
	ds_read_b128 v[170:173], v157 offset:3072
	s_add_u32 s14, s12, 0xfff80080
	s_addc_u32 s15, s13, -1
	s_cmp_eq_u32 s51, 28
	s_cselect_b32 s17, s53, s15
	s_cselect_b32 s16, s52, s14
	s_cselect_b32 s15, s55, s49
	s_cselect_b32 s14, s54, s11
	v_lshl_add_u64 v[134:135], s[12:13], 0, v[146:147]
	s_add_i32 m0, s72, 0xc000
	ds_read_b128 v[174:177], v158
	ds_read_b128 v[178:181], v158 offset:1024
	ds_read_b128 v[182:185], v158 offset:2048
	ds_read_b128 v[186:189], v158 offset:3072
	ds_read_b128 v[190:193], v158 offset:4096
	ds_read_b128 v[206:209], v158 offset:5120
	ds_read_b128 v[210:213], v158 offset:6144
	ds_read_b128 v[214:217], v158 offset:7168
	global_load_lds_dwordx4 v[134:135], off
	v_lshl_add_u64 v[134:135], s[12:13], 0, v[148:149]
	s_add_i32 m0, s72, 0xe000
	s_nop 0
	global_load_lds_dwordx4 v[134:135], off
	s_waitcnt lgkmcnt(8)
	s_barrier
	s_waitcnt lgkmcnt(0)
	s_setprio 1
	s_waitcnt lgkmcnt(0)
	v_mfma_f32_16x16x32_bf16 v[124:127], v[130:133], v[174:177], v[124:127]
	v_mfma_f32_16x16x32_bf16 v[120:123], v[166:169], v[174:177], v[120:123]
	v_mfma_f32_16x16x32_bf16 v[108:111], v[130:133], v[182:185], v[108:111]
	v_mfma_f32_16x16x32_bf16 v[104:107], v[166:169], v[182:185], v[104:107]
	v_mfma_f32_16x16x32_bf16 v[92:95], v[130:133], v[190:193], v[92:95]
	v_mfma_f32_16x16x32_bf16 v[88:91], v[166:169], v[190:193], v[88:91]
	v_mfma_f32_16x16x32_bf16 v[76:79], v[130:133], v[210:213], v[76:79]
	v_mfma_f32_16x16x32_bf16 v[72:75], v[166:169], v[210:213], v[72:75]
	v_mfma_f32_16x16x32_bf16 v[124:127], v[162:165], v[178:181], v[124:127]
	v_mfma_f32_16x16x32_bf16 v[120:123], v[170:173], v[178:181], v[120:123]
	v_mfma_f32_16x16x32_bf16 v[108:111], v[162:165], v[186:189], v[108:111]
	v_mfma_f32_16x16x32_bf16 v[104:107], v[170:173], v[186:189], v[104:107]
	v_mfma_f32_16x16x32_bf16 v[92:95], v[162:165], v[206:209], v[92:95]
	v_mfma_f32_16x16x32_bf16 v[88:91], v[170:173], v[206:209], v[88:91]
	v_mfma_f32_16x16x32_bf16 v[76:79], v[162:165], v[214:217], v[76:79]
	v_mfma_f32_16x16x32_bf16 v[72:75], v[170:173], v[214:217], v[72:75]
	s_setprio 0
	s_barrier
	s_add_i32 s56, s39, s71
	v_lshl_add_u64 v[134:135], s[14:15], 0, v[200:201]
	s_mov_b32 m0, s56
	ds_read_b128 v[218:221], v159
	ds_read_b128 v[230:233], v159 offset:1024
	ds_read_b128 v[234:237], v159 offset:2048
	ds_read_b128 v[238:241], v159 offset:3072
	global_load_lds_dwordx4 v[134:135], off
	v_lshl_add_u64 v[194:195], s[14:15], 0, v[204:205]
	s_add_i32 m0, s56, 0x2000
	s_nop 0
	global_load_lds_dwordx4 v[194:195], off
	s_barrier
	s_waitcnt lgkmcnt(0)
	s_setprio 1
	s_waitcnt lgkmcnt(0)
	v_mfma_f32_16x16x32_bf16 v[116:119], v[218:221], v[174:177], v[116:119]
	v_mfma_f32_16x16x32_bf16 v[112:115], v[234:237], v[174:177], v[112:115]
	v_mfma_f32_16x16x32_bf16 v[100:103], v[218:221], v[182:185], v[100:103]
	v_mfma_f32_16x16x32_bf16 v[96:99], v[234:237], v[182:185], v[96:99]
	v_mfma_f32_16x16x32_bf16 v[84:87], v[218:221], v[190:193], v[84:87]
	v_mfma_f32_16x16x32_bf16 v[80:83], v[234:237], v[190:193], v[80:83]
	v_mfma_f32_16x16x32_bf16 v[68:71], v[218:221], v[210:213], v[68:71]
	v_mfma_f32_16x16x32_bf16 v[64:67], v[234:237], v[210:213], v[64:67]
	v_mfma_f32_16x16x32_bf16 v[116:119], v[230:233], v[178:181], v[116:119]
	v_mfma_f32_16x16x32_bf16 v[112:115], v[238:241], v[178:181], v[112:115]
	v_mfma_f32_16x16x32_bf16 v[100:103], v[230:233], v[186:189], v[100:103]
	v_mfma_f32_16x16x32_bf16 v[96:99], v[238:241], v[186:189], v[96:99]
	v_mfma_f32_16x16x32_bf16 v[84:87], v[230:233], v[206:209], v[84:87]
	v_mfma_f32_16x16x32_bf16 v[80:83], v[238:241], v[206:209], v[80:83]
	v_mfma_f32_16x16x32_bf16 v[68:71], v[230:233], v[214:217], v[68:71]
	v_mfma_f32_16x16x32_bf16 v[64:67], v[238:241], v[214:217], v[64:67]
	s_setprio 0
	s_mov_b32 m0, s72
	v_lshl_add_u64 v[242:243], s[16:17], 0, v[198:199]
	s_barrier
	ds_read_b128 v[174:177], v158 offset:16384
	ds_read_b128 v[178:181], v158 offset:17408
	ds_read_b128 v[182:185], v158 offset:18432
	ds_read_b128 v[186:189], v158 offset:19456
	ds_read_b128 v[190:193], v158 offset:20480
	ds_read_b128 v[206:209], v158 offset:21504
	ds_read_b128 v[210:213], v158 offset:22528
	ds_read_b128 v[214:217], v158 offset:23552
	global_load_lds_dwordx4 v[242:243], off
	v_lshl_add_u64 v[244:245], s[16:17], 0, v[202:203]
	s_mov_b32 m0, s73
	s_nop 0
	global_load_lds_dwordx4 v[244:245], off
	s_barrier
	s_waitcnt lgkmcnt(0)
	s_setprio 1
	s_waitcnt lgkmcnt(0)
	v_mfma_f32_16x16x32_bf16 v[60:63], v[130:133], v[174:177], v[60:63]
	v_mfma_f32_16x16x32_bf16 v[56:59], v[166:169], v[174:177], v[56:59]
	v_mfma_f32_16x16x32_bf16 v[44:47], v[130:133], v[182:185], v[44:47]
	v_mfma_f32_16x16x32_bf16 v[40:43], v[166:169], v[182:185], v[40:43]
	v_mfma_f32_16x16x32_bf16 v[28:31], v[130:133], v[190:193], v[28:31]
	v_mfma_f32_16x16x32_bf16 v[24:27], v[166:169], v[190:193], v[24:27]
	v_mfma_f32_16x16x32_bf16 v[12:15], v[130:133], v[210:213], v[12:15]
	v_mfma_f32_16x16x32_bf16 v[8:11], v[166:169], v[210:213], v[8:11]
	v_mfma_f32_16x16x32_bf16 v[60:63], v[162:165], v[178:181], v[60:63]
	v_mfma_f32_16x16x32_bf16 v[56:59], v[170:173], v[178:181], v[56:59]
	v_mfma_f32_16x16x32_bf16 v[44:47], v[162:165], v[186:189], v[44:47]
	v_mfma_f32_16x16x32_bf16 v[40:43], v[170:173], v[186:189], v[40:43]
	v_mfma_f32_16x16x32_bf16 v[28:31], v[162:165], v[206:209], v[28:31]
	v_mfma_f32_16x16x32_bf16 v[24:27], v[170:173], v[206:209], v[24:27]
	v_mfma_f32_16x16x32_bf16 v[12:15], v[162:165], v[214:217], v[12:15]
	v_mfma_f32_16x16x32_bf16 v[8:11], v[170:173], v[214:217], v[8:11]
	s_setprio 0
	s_barrier
; #define G8_STAGE(bufoff, gbase, voff) do { _Pragma("unroll") for (int _i = 0; _i < 2; ++_i) \
;     __builtin_amdgcn_global_load_lds((const unsigned*)((const char*)(gbase) + (voff)[_i]), (G8_LAS unsigned*)(lds + (bufoff) + ldsw + _i * 8192), 16, 0, 0); } while (0)
; #define G8_LDA(dst, b, h) do { _Pragma("unroll") for (int m = 0; m < 4; ++m) _Pragma("unroll") for (int k = 0; k < 2; ++k) dst[m][k] = *(const G8_LAS bf16x8*)(lds + G8_SA(b, h) + aoff + m * 2048 + k * 1024); } while (0)
; #define G8_LDB(dst, b, h) do { _Pragma("unroll") for (int n = 0; n < 2; ++n) _Pragma("unroll") for (int k = 0; k < 2; ++k) dst[n][k] = *(const G8_LAS bf16x8*)(lds + G8_SB(b, h) + boff + n * 2048 + k * 1024); } while (0)
; #define G8_MMA(ai, bj, At, Bt) do { __builtin_amdgcn_s_setprio(1); _Pragma("unroll") for (int m = 0; m < 4; ++m) _Pragma("unroll") for (int n = 0; n < 2; ++n) _Pragma("unroll") for (int k = 0; k < 2; ++k) \
;     acc[ai][bj][m][n] = __builtin_amdgcn_mfma_f32_16x16x32_bf16(Bt[n][k], At[m][k], acc[ai][bj][m][n], 0, 0, 0); __builtin_amdgcn_s_setprio(0); } while (0)
; #define G8_WAIT_V(n) asm volatile("s_waitcnt vmcnt(" #n ")" ::: "memory")
; #define G8_WAIT_L(n) asm volatile("s_waitcnt lgkmcnt(" #n ")" ::: "memory")
; #define G8_BAR __builtin_amdgcn_s_barrier()
; #define G8_SCHED __builtin_amdgcn_sched_barrier(0)
; template <int LD, class Sched, class Epi>
; DI void gemm_phase(G8_LAS unsigned char* lds, const int K, const Sched& S, const Epi& E) {
;     ...
;       G8_WAIT_V(6); G8_BAR; G8_MMA(1, 1, At, B1); G8_BAR;
;       G8_LDB(B0, 1, 0); G8_SCHED; G8_LDA(At, 1, 0); G8_STAGE(G8_SA(0, 1), a2 + hstep, voffA);
;       G8_WAIT_L(8); G8_BAR; G8_WAIT_L(0); G8_MMA(0, 0, At, B0); G8_BAR; G8_SCHED;
;       G8_LDB(B1, 1, 1); G8_STAGE(G8_SB(1, 0), b3, voffB);
;       G8_BAR; G8_WAIT_L(0); G8_MMA(0, 1, At, B1); G8_BAR;
;       G8_LDA(At, 1, 1); G8_STAGE(G8_SA(1, 0), a3, voffA);
;       G8_BAR; G8_WAIT_L(0); G8_MMA(1, 0, At, B0); G8_BAR; G8_SCHED;
;       G8_STAGE(G8_SB(1, 1), b3 + hstep, voffB);
	s_add_u32 s56, s14, 0x80000
	s_addc_u32 s57, s15, 0
	s_add_i32 s58, s81, s71
	v_lshl_add_u64 v[130:131], s[56:57], 0, v[200:201]
	s_mov_b32 m0, s58
	s_nop 0
	global_load_lds_dwordx4 v[130:131], off
	v_lshl_add_u64 v[130:131], s[56:57], 0, v[204:205]
	s_add_i32 m0, s58, 0x2000
	s_nop 0
	global_load_lds_dwordx4 v[130:131], off
	s_waitcnt vmcnt(6)
	s_barrier
	s_setprio 1
	v_mfma_f32_16x16x32_bf16 v[52:55], v[218:221], v[174:177], v[52:55]
	v_mfma_f32_16x16x32_bf16 v[48:51], v[234:237], v[174:177], v[48:51]
	v_mfma_f32_16x16x32_bf16 v[36:39], v[218:221], v[182:185], v[36:39]
	v_mfma_f32_16x16x32_bf16 v[32:35], v[234:237], v[182:185], v[32:35]
	v_mfma_f32_16x16x32_bf16 v[20:23], v[218:221], v[190:193], v[20:23]
	v_mfma_f32_16x16x32_bf16 v[16:19], v[234:237], v[190:193], v[16:19]
	v_mfma_f32_16x16x32_bf16 v[4:7], v[218:221], v[210:213], v[4:7]
	v_mfma_f32_16x16x32_bf16 v[0:3], v[234:237], v[210:213], v[0:3]
	v_mfma_f32_16x16x32_bf16 v[52:55], v[230:233], v[178:181], v[52:55]
	v_mfma_f32_16x16x32_bf16 v[48:51], v[238:241], v[178:181], v[48:51]
	v_mfma_f32_16x16x32_bf16 v[36:39], v[230:233], v[186:189], v[36:39]
	v_mfma_f32_16x16x32_bf16 v[32:35], v[238:241], v[186:189], v[32:35]
	v_mfma_f32_16x16x32_bf16 v[20:23], v[230:233], v[206:209], v[20:23]
	v_mfma_f32_16x16x32_bf16 v[16:19], v[238:241], v[206:209], v[16:19]
	v_mfma_f32_16x16x32_bf16 v[4:7], v[230:233], v[214:217], v[4:7]
	v_mfma_f32_16x16x32_bf16 v[0:3], v[238:241], v[214:217], v[0:3]
	s_setprio 0
	s_add_i32 s56, 0, 0x18000
	v_add_u32_e32 v129, s56, v155
	s_barrier
	ds_read_b128 v[130:133], v129
	ds_read_b128 v[162:165], v129 offset:1024
	ds_read_b128 v[166:169], v129 offset:2048
	ds_read_b128 v[170:173], v129 offset:3072
	s_add_u32 s16, s16, 0x80000
	s_addc_u32 s17, s17, 0
	s_mov_b32 m0, s74
	v_lshl_add_u64 v[218:219], s[16:17], 0, v[198:199]
	ds_read_b128 v[174:177], v158 offset:32768
	ds_read_b128 v[178:181], v158 offset:33792
	ds_read_b128 v[182:185], v158 offset:34816
	ds_read_b128 v[186:189], v158 offset:35840
	ds_read_b128 v[190:193], v158 offset:36864
	ds_read_b128 v[206:209], v158 offset:37888
	ds_read_b128 v[210:213], v158 offset:38912
	ds_read_b128 v[214:217], v158 offset:39936
	global_load_lds_dwordx4 v[218:219], off
	v_lshl_add_u64 v[218:219], s[16:17], 0, v[202:203]
	s_mov_b32 m0, s75
	s_nop 0
	global_load_lds_dwordx4 v[218:219], off
	s_waitcnt lgkmcnt(8)
	s_barrier
	s_waitcnt lgkmcnt(0)
	s_setprio 1
	s_waitcnt lgkmcnt(0)
	v_mfma_f32_16x16x32_bf16 v[124:127], v[130:133], v[174:177], v[124:127]
	v_mfma_f32_16x16x32_bf16 v[120:123], v[166:169], v[174:177], v[120:123]
	v_mfma_f32_16x16x32_bf16 v[108:111], v[130:133], v[182:185], v[108:111]
	v_mfma_f32_16x16x32_bf16 v[104:107], v[166:169], v[182:185], v[104:107]
	v_mfma_f32_16x16x32_bf16 v[92:95], v[130:133], v[190:193], v[92:95]
	v_mfma_f32_16x16x32_bf16 v[88:91], v[166:169], v[190:193], v[88:91]
	v_mfma_f32_16x16x32_bf16 v[76:79], v[130:133], v[210:213], v[76:79]
	v_mfma_f32_16x16x32_bf16 v[72:75], v[166:169], v[210:213], v[72:75]
	v_mfma_f32_16x16x32_bf16 v[124:127], v[162:165], v[178:181], v[124:127]
	v_mfma_f32_16x16x32_bf16 v[120:123], v[170:173], v[178:181], v[120:123]
	v_mfma_f32_16x16x32_bf16 v[108:111], v[162:165], v[186:189], v[108:111]
	v_mfma_f32_16x16x32_bf16 v[104:107], v[170:173], v[186:189], v[104:107]
	v_mfma_f32_16x16x32_bf16 v[92:95], v[162:165], v[206:209], v[92:95]
	v_mfma_f32_16x16x32_bf16 v[88:91], v[170:173], v[206:209], v[88:91]
	v_mfma_f32_16x16x32_bf16 v[76:79], v[162:165], v[214:217], v[76:79]
	v_mfma_f32_16x16x32_bf16 v[72:75], v[170:173], v[214:217], v[72:75]
	s_setprio 0
	s_barrier
	s_add_i32 s16, 0, 0x1c000
	s_add_i32 s17, s56, s71
	v_add_u32_e32 v129, s16, v155
	v_lshl_add_u64 v[134:135], v[134:135], 0, s[2:3]
	s_mov_b32 m0, s17
	ds_read_b128 v[218:221], v129
	ds_read_b128 v[230:233], v129 offset:1024
	ds_read_b128 v[234:237], v129 offset:2048
	ds_read_b128 v[238:241], v129 offset:3072
	global_load_lds_dwordx4 v[134:135], off
	v_lshl_add_u64 v[134:135], v[194:195], 0, s[2:3]
	s_add_i32 m0, s17, 0x2000
	s_nop 0
	global_load_lds_dwordx4 v[134:135], off
	s_barrier
	s_waitcnt lgkmcnt(0)
	s_setprio 1
	s_waitcnt lgkmcnt(0)
	v_mfma_f32_16x16x32_bf16 v[116:119], v[218:221], v[174:177], v[116:119]
	v_mfma_f32_16x16x32_bf16 v[112:115], v[234:237], v[174:177], v[112:115]
	v_mfma_f32_16x16x32_bf16 v[100:103], v[218:221], v[182:185], v[100:103]
	v_mfma_f32_16x16x32_bf16 v[96:99], v[234:237], v[182:185], v[96:99]
	v_mfma_f32_16x16x32_bf16 v[84:87], v[218:221], v[190:193], v[84:87]
	v_mfma_f32_16x16x32_bf16 v[80:83], v[234:237], v[190:193], v[80:83]
	v_mfma_f32_16x16x32_bf16 v[68:71], v[218:221], v[210:213], v[68:71]
	v_mfma_f32_16x16x32_bf16 v[64:67], v[234:237], v[210:213], v[64:67]
	v_mfma_f32_16x16x32_bf16 v[116:119], v[230:233], v[178:181], v[116:119]
	v_mfma_f32_16x16x32_bf16 v[112:115], v[238:241], v[178:181], v[112:115]
	v_mfma_f32_16x16x32_bf16 v[100:103], v[230:233], v[186:189], v[100:103]
	v_mfma_f32_16x16x32_bf16 v[96:99], v[238:241], v[186:189], v[96:99]
	v_mfma_f32_16x16x32_bf16 v[84:87], v[230:233], v[206:209], v[84:87]
	v_mfma_f32_16x16x32_bf16 v[80:83], v[238:241], v[206:209], v[80:83]
	v_mfma_f32_16x16x32_bf16 v[68:71], v[230:233], v[214:217], v[68:71]
	v_mfma_f32_16x16x32_bf16 v[64:67], v[238:241], v[214:217], v[64:67]
	s_setprio 0
	s_mov_b32 m0, s77
	v_lshl_add_u64 v[134:135], v[242:243], 0, s[2:3]
	s_barrier
	ds_read_b128 v[174:177], v158 offset:49152
	ds_read_b128 v[178:181], v158 offset:50176
	ds_read_b128 v[182:185], v158 offset:51200
	ds_read_b128 v[186:189], v158 offset:52224
	ds_read_b128 v[190:193], v158 offset:53248
	ds_read_b128 v[206:209], v158 offset:54272
	ds_read_b128 v[210:213], v158 offset:55296
	ds_read_b128 v[214:217], v158 offset:56320
	global_load_lds_dwordx4 v[134:135], off
	v_lshl_add_u64 v[134:135], v[244:245], 0, s[2:3]
	s_mov_b32 m0, s78
	s_nop 0
	global_load_lds_dwordx4 v[134:135], off
	s_barrier
; #define G8_STAGE(bufoff, gbase, voff) do { _Pragma("unroll") for (int _i = 0; _i < 2; ++_i) \
;     __builtin_amdgcn_global_load_lds((const unsigned*)((const char*)(gbase) + (voff)[_i]), (G8_LAS unsigned*)(lds + (bufoff) + ldsw + _i * 8192), 16, 0, 0); } while (0)
; #define G8_LDA(dst, b, h) do { _Pragma("unroll") for (int m = 0; m < 4; ++m) _Pragma("unroll") for (int k = 0; k < 2; ++k) dst[m][k] = *(const G8_LAS bf16x8*)(lds + G8_SA(b, h) + aoff + m * 2048 + k * 1024); } while (0)
; #define G8_MMA(ai, bj, At, Bt) do { __builtin_amdgcn_s_setprio(1); _Pragma("unroll") for (int m = 0; m < 4; ++m) _Pragma("unroll") for (int n = 0; n < 2; ++n) _Pragma("unroll") for (int k = 0; k < 2; ++k) \
;     acc[ai][bj][m][n] = __builtin_amdgcn_mfma_f32_16x16x32_bf16(Bt[n][k], At[m][k], acc[ai][bj][m][n], 0, 0, 0); __builtin_amdgcn_s_setprio(0); } while (0)
; #define G8_WAIT_V(n) asm volatile("s_waitcnt vmcnt(" #n ")" ::: "memory")
; #define G8_WAIT_L(n) asm volatile("s_waitcnt lgkmcnt(" #n ")" ::: "memory")
; #define G8_BAR __builtin_amdgcn_s_barrier()
; #define G8_SCHED __builtin_amdgcn_sched_barrier(0)
; template <int LD, class Sched, class Epi>
; DI void gemm_phase(G8_LAS unsigned char* lds, const int K, const Sched& S, const Epi& E) {
;     ...
;       G8_LDA(At, 1, 1); G8_STAGE(G8_SA(1, 0), a3, voffA);
;       G8_BAR; G8_WAIT_L(0); G8_MMA(1, 0, At, B0); G8_BAR; G8_SCHED;
;       G8_STAGE(G8_SB(1, 1), b3 + hstep, voffB);
;       G8_WAIT_V(6); G8_BAR; G8_MMA(1, 1, At, B1); G8_BAR;
;     }
;     E(acc, cur, wr, wc, fr, fq);
	s_waitcnt lgkmcnt(0)
	s_setprio 1
	s_waitcnt lgkmcnt(0)
	v_mfma_f32_16x16x32_bf16 v[60:63], v[130:133], v[174:177], v[60:63]
	v_mfma_f32_16x16x32_bf16 v[56:59], v[166:169], v[174:177], v[56:59]
	v_mfma_f32_16x16x32_bf16 v[44:47], v[130:133], v[182:185], v[44:47]
	v_mfma_f32_16x16x32_bf16 v[40:43], v[166:169], v[182:185], v[40:43]
	v_mfma_f32_16x16x32_bf16 v[28:31], v[130:133], v[190:193], v[28:31]
	v_mfma_f32_16x16x32_bf16 v[24:27], v[166:169], v[190:193], v[24:27]
	v_mfma_f32_16x16x32_bf16 v[12:15], v[130:133], v[210:213], v[12:15]
	v_mfma_f32_16x16x32_bf16 v[8:11], v[166:169], v[210:213], v[8:11]
	v_mfma_f32_16x16x32_bf16 v[60:63], v[162:165], v[178:181], v[60:63]
	v_mfma_f32_16x16x32_bf16 v[56:59], v[170:173], v[178:181], v[56:59]
	v_mfma_f32_16x16x32_bf16 v[44:47], v[162:165], v[186:189], v[44:47]
	v_mfma_f32_16x16x32_bf16 v[40:43], v[170:173], v[186:189], v[40:43]
	v_mfma_f32_16x16x32_bf16 v[28:31], v[162:165], v[206:209], v[28:31]
	v_mfma_f32_16x16x32_bf16 v[24:27], v[170:173], v[206:209], v[24:27]
	v_mfma_f32_16x16x32_bf16 v[12:15], v[162:165], v[214:217], v[12:15]
	v_mfma_f32_16x16x32_bf16 v[8:11], v[170:173], v[214:217], v[8:11]
	s_setprio 0
	s_barrier
	s_add_u32 s14, s14, 0x80080
	s_addc_u32 s15, s15, 0
	s_add_i32 s16, s16, s71
	v_lshl_add_u64 v[130:131], s[14:15], 0, v[200:201]
	s_mov_b32 m0, s16
	s_nop 0
	global_load_lds_dwordx4 v[130:131], off
	v_lshl_add_u64 v[130:131], s[14:15], 0, v[204:205]
	s_add_i32 m0, s16, 0x2000
	s_nop 0
	global_load_lds_dwordx4 v[130:131], off
	s_waitcnt vmcnt(6)
	s_barrier
	s_setprio 1
	v_mfma_f32_16x16x32_bf16 v[52:55], v[218:221], v[174:177], v[52:55]
	v_mfma_f32_16x16x32_bf16 v[48:51], v[234:237], v[174:177], v[48:51]
	v_mfma_f32_16x16x32_bf16 v[36:39], v[218:221], v[182:185], v[36:39]
	v_mfma_f32_16x16x32_bf16 v[32:35], v[234:237], v[182:185], v[32:35]
	v_mfma_f32_16x16x32_bf16 v[20:23], v[218:221], v[190:193], v[20:23]
	v_mfma_f32_16x16x32_bf16 v[16:19], v[234:237], v[190:193], v[16:19]
	v_mfma_f32_16x16x32_bf16 v[4:7], v[218:221], v[210:213], v[4:7]
	v_mfma_f32_16x16x32_bf16 v[0:3], v[234:237], v[210:213], v[0:3]
	v_mfma_f32_16x16x32_bf16 v[52:55], v[230:233], v[178:181], v[52:55]
	v_mfma_f32_16x16x32_bf16 v[48:51], v[238:241], v[178:181], v[48:51]
	v_mfma_f32_16x16x32_bf16 v[36:39], v[230:233], v[186:189], v[36:39]
	v_mfma_f32_16x16x32_bf16 v[32:35], v[238:241], v[186:189], v[32:35]
	v_mfma_f32_16x16x32_bf16 v[20:23], v[230:233], v[206:209], v[20:23]
	v_mfma_f32_16x16x32_bf16 v[16:19], v[238:241], v[206:209], v[16:19]
	v_mfma_f32_16x16x32_bf16 v[4:7], v[230:233], v[214:217], v[4:7]
	v_mfma_f32_16x16x32_bf16 v[0:3], v[238:241], v[214:217], v[0:3]
	s_setprio 0
	s_add_i32 s51, s51, 2
	s_add_u32 s12, s12, 0x100
	s_addc_u32 s13, s13, 0
	s_add_u32 s11, s11, 0x100
	s_addc_u32 s49, s49, 0
	s_cmp_gt_u32 s51, 29
	s_barrier
	s_cbranch_scc0 .LBB0_92
	v_cmp_eq_u32_e32 vcc, 0, v128
	s_lshl_b32 s13, s10, 8
	s_lshl_b32 s12, s33, 8
	s_cbranch_vccnz .LBB0_95
; DI unsigned pk2(float a, float b) { f32x2 v = {a, b}; bf16x2_t r = __builtin_convertvector(v, bf16x2_t); return __builtin_bit_cast(unsigned, r); }
;   __device__ __forceinline__ void operator()(const f32x4 (&acc)[2][2][4][2], const g8::Unit& u, int wr, int wc, int fr, int fq) const {
;     ...
;     if (u.kind) {
;       u16* base; int f0, nf;
;       if (pn < 12) { base = p.VaT; f0 = n0 - 2048; nf = 1024; }
;       else if (pn == 23) { base = p.VsT; f0 = 0; nf = 256; }
;       else { base = p.VwT; f0 = 0; nf = 256; }
;       const int s0 = (m0 & (SQ - 1)) + 32 * wc + 16 * (fq & 1) + 4 * (fq >> 1);
; #pragma unroll
;       for (int ai = 0; ai < 2; ++ai)
; #pragma unroll
;         for (int m = 0; m < 4; ++m) {
;           const int f = f0 + 128 * ai + 64 * wr + 16 * m + fr;
;           u16* rowp = base + ((size_t)b * nf + f) * SQ + s0;
; #pragma unroll
;           for (int bj = 0; bj < 2; ++bj) {
;             const f32x4 v0 = acc[ai][bj][m][0], v1 = acc[ai][bj][m][1];
;             *(uint2*)(rowp + 128 * bj) = make_uint2(pk2(v0[0], v0[1]), pk2(v0[2], v0[3]));
;             *(uint2*)(rowp + 128 * bj + 8) = make_uint2(pk2(v1[0], v1[1]), pk2(v1[2], v1[3]));
;           }
;         }
;       return;
	s_ashr_i32 s10, s10, 5
	s_add_i32 s11, s12, 0xfffff800
	s_cmp_eq_u32 s33, 23
	s_cselect_b32 s14, s82, 0x128
	s_cmp_lt_i32 s33, 12
	s_cselect_b32 s14, 0xe8, s14
	s_cselect_b32 s11, s11, 0
	s_cselect_b32 s16, 10, 8
	s_add_u32 s14, s92, s14
	s_addc_u32 s15, s93, 0
	s_load_dwordx2 s[14:15], s[14:15], 0x0
	s_and_b32 s17, s13, 0x1f00
	v_or_b32_e32 v129, s17, v156
	v_add_u32_e32 v128, s11, v154
	s_ashr_i32 s11, s10, 31
	s_lshl_b64 s[10:11], s[10:11], s16
	v_lshlrev_b32_e32 v130, 1, v129
	v_and_b32_e32 v134, 32, v160
	v_lshrrev_b32_e32 v134, 2, v134
	v_add_u32_e32 v130, v130, v134
	v_ashrrev_i32_e32 v129, 31, v128
	v_mov_b32_e32 v131, v137
	v_lshl_add_u64 v[132:133], s[10:11], 0, v[128:129]
	s_waitcnt lgkmcnt(0)
	v_lshl_add_u64 v[130:131], s[14:15], 0, v[130:131]
	v_lshlrev_b64 v[132:133], 14, v[132:133]
	v_lshl_add_u64 v[132:133], v[130:131], 0, v[132:133]
	v_cvt_pk_bf16_f32 v124, v124, v125
	v_cvt_pk_bf16_f32 v125, v126, v127
	v_cvt_pk_bf16_f32 v126, v120, v121
	v_cvt_pk_bf16_f32 v127, v122, v123
	v_cvt_pk_bf16_f32 v116, v116, v117
	v_cvt_pk_bf16_f32 v117, v118, v119
	v_cvt_pk_bf16_f32 v118, v112, v113
	v_cvt_pk_bf16_f32 v119, v114, v115
	s_nop 1
	v_permlane32_swap_b32_e32 v124, v126
	v_permlane32_swap_b32_e32 v125, v127
	v_permlane32_swap_b32_e32 v116, v118
	v_permlane32_swap_b32_e32 v117, v119
	global_store_dwordx4 v[132:133], v[124:127], off
	global_store_dwordx4 v[132:133], v[116:119], off offset:256
	v_or_b32_e32 v132, 16, v128
	v_ashrrev_i32_e32 v133, 31, v132
	v_lshl_add_u64 v[132:133], s[10:11], 0, v[132:133]
	v_lshlrev_b64 v[132:133], 14, v[132:133]
	v_lshl_add_u64 v[132:133], v[130:131], 0, v[132:133]
	v_cvt_pk_bf16_f32 v108, v108, v109
	v_cvt_pk_bf16_f32 v109, v110, v111
	v_cvt_pk_bf16_f32 v110, v104, v105
	v_cvt_pk_bf16_f32 v111, v106, v107
	v_cvt_pk_bf16_f32 v100, v100, v101
	v_cvt_pk_bf16_f32 v101, v102, v103
	v_cvt_pk_bf16_f32 v102, v96, v97
	v_cvt_pk_bf16_f32 v103, v98, v99
	s_nop 1
	v_permlane32_swap_b32_e32 v108, v110
	v_permlane32_swap_b32_e32 v109, v111
	v_permlane32_swap_b32_e32 v100, v102
	v_permlane32_swap_b32_e32 v101, v103
	global_store_dwordx4 v[132:133], v[108:111], off
	global_store_dwordx4 v[132:133], v[100:103], off offset:256
	v_or_b32_e32 v132, 32, v128
	v_ashrrev_i32_e32 v133, 31, v132
	v_lshl_add_u64 v[132:133], s[10:11], 0, v[132:133]
	v_lshlrev_b64 v[132:133], 14, v[132:133]
	v_lshl_add_u64 v[132:133], v[130:131], 0, v[132:133]
	v_cvt_pk_bf16_f32 v92, v92, v93
	v_cvt_pk_bf16_f32 v93, v94, v95
	v_cvt_pk_bf16_f32 v94, v88, v89
	v_cvt_pk_bf16_f32 v95, v90, v91
	v_cvt_pk_bf16_f32 v84, v84, v85
	v_cvt_pk_bf16_f32 v85, v86, v87
	v_cvt_pk_bf16_f32 v86, v80, v81
	v_cvt_pk_bf16_f32 v87, v82, v83
	s_nop 1
	v_permlane32_swap_b32_e32 v92, v94
	v_permlane32_swap_b32_e32 v93, v95
	v_permlane32_swap_b32_e32 v84, v86
	v_permlane32_swap_b32_e32 v85, v87
	global_store_dwordx4 v[132:133], v[92:95], off
	global_store_dwordx4 v[132:133], v[84:87], off offset:256
	v_or_b32_e32 v132, 48, v128
	v_ashrrev_i32_e32 v133, 31, v132
	v_lshl_add_u64 v[132:133], s[10:11], 0, v[132:133]
	v_lshlrev_b64 v[132:133], 14, v[132:133]
	v_lshl_add_u64 v[132:133], v[130:131], 0, v[132:133]
	v_cvt_pk_bf16_f32 v76, v76, v77
	v_cvt_pk_bf16_f32 v77, v78, v79
	v_cvt_pk_bf16_f32 v78, v72, v73
	v_cvt_pk_bf16_f32 v79, v74, v75
	v_cvt_pk_bf16_f32 v68, v68, v69
	v_cvt_pk_bf16_f32 v69, v70, v71
	v_cvt_pk_bf16_f32 v70, v64, v65
	v_cvt_pk_bf16_f32 v71, v66, v67
	s_nop 1
	v_permlane32_swap_b32_e32 v76, v78
	v_permlane32_swap_b32_e32 v77, v79
	v_permlane32_swap_b32_e32 v68, v70
	v_permlane32_swap_b32_e32 v69, v71
	global_store_dwordx4 v[132:133], v[76:79], off
	global_store_dwordx4 v[132:133], v[68:71], off offset:256
	v_add_u32_e32 v132, 0x80, v128
	v_ashrrev_i32_e32 v133, 31, v132
	v_lshl_add_u64 v[132:133], s[10:11], 0, v[132:133]
	v_lshlrev_b64 v[132:133], 14, v[132:133]
	v_lshl_add_u64 v[132:133], v[130:131], 0, v[132:133]
	v_cvt_pk_bf16_f32 v60, v60, v61
	v_cvt_pk_bf16_f32 v61, v62, v63
	v_cvt_pk_bf16_f32 v62, v56, v57
	v_cvt_pk_bf16_f32 v63, v58, v59
	v_cvt_pk_bf16_f32 v52, v52, v53
	v_cvt_pk_bf16_f32 v53, v54, v55
	v_cvt_pk_bf16_f32 v54, v48, v49
	v_cvt_pk_bf16_f32 v55, v50, v51
	s_nop 1
	v_permlane32_swap_b32_e32 v60, v62
	v_permlane32_swap_b32_e32 v61, v63
	v_permlane32_swap_b32_e32 v52, v54
	v_permlane32_swap_b32_e32 v53, v55
	global_store_dwordx4 v[132:133], v[60:63], off
	global_store_dwordx4 v[132:133], v[52:55], off offset:256
	v_add_u32_e32 v132, 0x90, v128
	v_ashrrev_i32_e32 v133, 31, v132
	v_lshl_add_u64 v[132:133], s[10:11], 0, v[132:133]
	v_lshlrev_b64 v[132:133], 14, v[132:133]
	v_lshl_add_u64 v[132:133], v[130:131], 0, v[132:133]
	v_cvt_pk_bf16_f32 v44, v44, v45
	v_cvt_pk_bf16_f32 v45, v46, v47
	v_cvt_pk_bf16_f32 v46, v40, v41
	v_cvt_pk_bf16_f32 v47, v42, v43
	v_cvt_pk_bf16_f32 v36, v36, v37
	v_cvt_pk_bf16_f32 v37, v38, v39
	v_cvt_pk_bf16_f32 v38, v32, v33
	v_cvt_pk_bf16_f32 v39, v34, v35
	s_nop 1
	v_permlane32_swap_b32_e32 v44, v46
	v_permlane32_swap_b32_e32 v45, v47
	v_permlane32_swap_b32_e32 v36, v38
	v_permlane32_swap_b32_e32 v37, v39
	global_store_dwordx4 v[132:133], v[44:47], off
	global_store_dwordx4 v[132:133], v[36:39], off offset:256
	v_add_u32_e32 v132, 0xa0, v128
	v_ashrrev_i32_e32 v133, 31, v132
	v_lshl_add_u64 v[132:133], s[10:11], 0, v[132:133]
	v_lshlrev_b64 v[132:133], 14, v[132:133]
	v_lshl_add_u64 v[132:133], v[130:131], 0, v[132:133]
	v_cvt_pk_bf16_f32 v28, v28, v29
	v_cvt_pk_bf16_f32 v29, v30, v31
	v_cvt_pk_bf16_f32 v30, v24, v25
	v_cvt_pk_bf16_f32 v31, v26, v27
	v_cvt_pk_bf16_f32 v20, v20, v21
	v_cvt_pk_bf16_f32 v21, v22, v23
	v_cvt_pk_bf16_f32 v22, v16, v17
	v_cvt_pk_bf16_f32 v23, v18, v19
	s_nop 1
	v_permlane32_swap_b32_e32 v28, v30
	v_permlane32_swap_b32_e32 v29, v31
	v_permlane32_swap_b32_e32 v20, v22
	v_permlane32_swap_b32_e32 v21, v23
	global_store_dwordx4 v[132:133], v[28:31], off
	global_store_dwordx4 v[132:133], v[20:23], off offset:256
	v_add_u32_e32 v132, 0xb0, v128
	v_ashrrev_i32_e32 v133, 31, v132
	v_lshl_add_u64 v[132:133], s[10:11], 0, v[132:133]
	v_lshlrev_b64 v[132:133], 14, v[132:133]
	v_lshl_add_u64 v[132:133], v[130:131], 0, v[132:133]
	v_cvt_pk_bf16_f32 v12, v12, v13
	v_cvt_pk_bf16_f32 v13, v14, v15
	v_cvt_pk_bf16_f32 v14, v8, v9
	v_cvt_pk_bf16_f32 v15, v10, v11
	v_cvt_pk_bf16_f32 v4, v4, v5
	v_cvt_pk_bf16_f32 v5, v6, v7
	v_cvt_pk_bf16_f32 v6, v0, v1
	v_cvt_pk_bf16_f32 v7, v2, v3
	s_nop 1
	v_permlane32_swap_b32_e32 v12, v14
	v_permlane32_swap_b32_e32 v13, v15
	v_permlane32_swap_b32_e32 v4, v6
	v_permlane32_swap_b32_e32 v5, v7
	global_store_dwordx4 v[132:133], v[12:15], off
	global_store_dwordx4 v[132:133], v[4:7], off offset:256
	s_cbranch_execnz .LBB0_88
	s_branch .LBB0_96
